# P9: unit-to-workgroup assignment rotated by 64 per round so the sixth-round units go to workgroups with fewer rope units
# baseline (speedup 1.0000x reference)
.LBB0_1046:
	s_add_i32 s77, s77, 1
	s_mul_i32 s6, s77, s78
	s_mul_hi_u32 s7, s77, s81
	s_add_i32 s7, s7, s6
	s_mul_i32 s6, s77, s81
	s_lshl_b32 s98, s77, 6
	s_add_u32 s98, s98, s2
	s_and_b32 s98, s98, 0xff
	s_add_u32 s58, s6, s98
	s_addc_u32 s59, s7, s3
	v_cmp_gt_i64_e64 s[6:7], s[58:59], v[140:141]
	s_and_b64 vcc, exec, s[6:7]
	s_mov_b64 s[60:61], -1
	s_cbranch_vccnz .LBB0_1049
	s_andn2_b64 vcc, exec, s[60:61]
	s_cbranch_vccz .LBB0_1050
